# final RMSNorm loop hand-pipelined, 2 rows per batch double-buffered, gains in registers
# speedup vs baseline: 1.0020x; 1.0020x over previous
; DI float bflo(unsigned w) { return __uint_as_float(w << 16); }
; DI float bfhi(unsigned w) { return __uint_as_float(w & 0xffff0000u); }
; __global__ void __launch_bounds__(512, 2) fwd_mega(Params p) {
;     ...
;   { int tidf = threadIdx.x; asm volatile("" : "+v"(tidf)); const int lane = tidf & 63; const int gw = bid * 8 + (tidf >> 6);
;     for (int m = gw; m < MTOK; m += 2 * NGW) {
;       const int m2 = (m + NGW < MTOK) ? m + NGW : m;
;       const float q1 = ssq[3 * MTOK + m], q2 = ssq[3 * MTOK + m2];
;       const u32x4* xr = (const u32x4*)(XB + (size_t)m * DM) + lane; const u32x4* xr2 = (const u32x4*)(XB + (size_t)m2 * DM) + lane;
;       const u32x4 va0 = xr[0], va1 = xr[64], vb0 = xr2[0], vb1 = xr2[64];
;       const f32x4* gr = (const f32x4*)p.final_norm;
; #pragma unroll
;       for (int rr = 0; rr < 2; ++rr) {
;         if (rr == 1 && m2 == m) break;
;         const float rstd = rsqrtf((rr ? q2 : q1) * (1.f / DM) + EPSN);
;         f32x4* orow = (f32x4*)(p.out + (size_t)(rr ? m2 : m) * DM);
; #pragma unroll
;         for (int j = 0; j < 2; ++j) { const u32x4 v = rr ? (j ? vb1 : vb0) : (j ? va1 : va0); const int c4 = (64 * j + lane) * 2;
;           const f32x4 g0 = gr[c4], g1 = gr[c4 + 1];
;           f32x4 o0, o1; o0[0] = bflo(v.x) * rstd * g0[0]; o0[1] = bfhi(v.x) * rstd * g0[1]; o0[2] = bflo(v.y) * rstd * g0[2]; o0[3] = bfhi(v.y) * rstd * g0[3];
;           o1[0] = bflo(v.z) * rstd * g1[0]; o1[1] = bfhi(v.z) * rstd * g1[1]; o1[2] = bflo(v.w) * rstd * g1[2]; o1[3] = bfhi(v.w) * rstd * g1[3];
;           __builtin_nontemporal_store(o0, &orow[c4]); __builtin_nontemporal_store(o1, &orow[c4 + 1]); }
;       }
;     } }
.Lfin_loop:
	s_lshl_b32 s18, s48, 1
	s_add_u32 s9, s8, s18
	s_min_u32 s12, s9, 0xffff
	s_lshl_b32 s13, s12, 11
	s_add_u32 s14, s72, s13
	s_addc_u32 s15, s73, 0
	global_load_dwordx4 v[120:123], v8, s[14:15]
	global_load_dwordx4 v[124:127], v8, s[14:15] offset:1024
	s_lshl_b32 s13, s12, 2
	s_add_u32 s14, s10, s13
	s_addc_u32 s15, s11, 0
	global_load_dword v128, v10, s[14:15]
	s_mul_i32 s12, s48, 1
	s_add_u32 s12, s12, s9
	s_min_u32 s12, s12, 0xffff
	s_lshl_b32 s13, s12, 11
	s_add_u32 s14, s72, s13
	s_addc_u32 s15, s73, 0
	global_load_dwordx4 v[130:133], v8, s[14:15]
	global_load_dwordx4 v[134:137], v8, s[14:15] offset:1024
	s_lshl_b32 s13, s12, 2
	s_add_u32 s14, s10, s13
	s_addc_u32 s15, s11, 0
	global_load_dword v138, v10, s[14:15]
	s_waitcnt vmcnt(6)
	s_mov_b32 s12, s8
	v_fmamk_f32 v20, v88, 0x3a800000, v18
	v_mul_f32_e32 v21, 0x4b800000, v20
	v_cmp_gt_f32_e32 vcc, s6, v20
	s_lshl_b32 s13, s12, 12
	s_add_u32 s16, s2, s13
	v_cndmask_b32_e32 v20, v20, v21, vcc
	v_rsq_f32_e32 v22, v20
	s_addc_u32 s17, s3, 0
	v_lshlrev_b32_e32 v24, 16, v80
	v_mul_f32_e32 v21, 0x45800000, v22
	v_and_b32_e32 v25, 0xffff0000, v80
	v_cndmask_b32_e32 v22, v22, v21, vcc
	v_lshlrev_b32_e32 v26, 16, v81
	v_and_b32_e32 v27, 0xffff0000, v81
	v_lshlrev_b32_e32 v28, 16, v82
	v_and_b32_e32 v29, 0xffff0000, v82
	v_lshlrev_b32_e32 v30, 16, v83
	v_and_b32_e32 v31, 0xffff0000, v83
	v_lshlrev_b32_e32 v32, 16, v84
	v_and_b32_e32 v33, 0xffff0000, v84
	v_lshlrev_b32_e32 v34, 16, v85
	v_and_b32_e32 v35, 0xffff0000, v85
	v_lshlrev_b32_e32 v36, 16, v86
	v_and_b32_e32 v37, 0xffff0000, v86
	v_lshlrev_b32_e32 v38, 16, v87
	v_and_b32_e32 v39, 0xffff0000, v87
	v_pk_mul_f32 v[24:25], v[22:23], v[24:25] op_sel_hi:[0,1]
	v_pk_mul_f32 v[26:27], v[22:23], v[26:27] op_sel_hi:[0,1]
	v_pk_mul_f32 v[28:29], v[22:23], v[28:29] op_sel_hi:[0,1]
	v_pk_mul_f32 v[30:31], v[22:23], v[30:31] op_sel_hi:[0,1]
	v_pk_mul_f32 v[32:33], v[22:23], v[32:33] op_sel_hi:[0,1]
	v_pk_mul_f32 v[34:35], v[22:23], v[34:35] op_sel_hi:[0,1]
	v_pk_mul_f32 v[36:37], v[22:23], v[36:37] op_sel_hi:[0,1]
	v_pk_mul_f32 v[38:39], v[22:23], v[38:39] op_sel_hi:[0,1]
	v_pk_mul_f32 v[24:25], v[64:65], v[24:25]
	v_pk_mul_f32 v[26:27], v[66:67], v[26:27]
	v_pk_mul_f32 v[28:29], v[68:69], v[28:29]
	v_pk_mul_f32 v[30:31], v[70:71], v[30:31]
	v_pk_mul_f32 v[32:33], v[72:73], v[32:33]
	v_pk_mul_f32 v[34:35], v[74:75], v[34:35]
	v_pk_mul_f32 v[36:37], v[76:77], v[36:37]
	v_pk_mul_f32 v[38:39], v[78:79], v[38:39]
	global_store_dwordx4 v9, v[24:27], s[16:17] nt
	global_store_dwordx4 v9, v[28:31], s[16:17] offset:16 nt
	global_store_dwordx4 v9, v[32:35], s[16:17] offset:2048 nt
	global_store_dwordx4 v9, v[36:39], s[16:17] offset:2064 nt
	s_mul_i32 s12, s48, 1
	s_add_u32 s12, s12, s8
	s_cmp_gt_u32 s12, 0xffff
	s_cbranch_scc1 .Lfin_skip_2
	v_fmamk_f32 v20, v98, 0x3a800000, v18
	v_mul_f32_e32 v21, 0x4b800000, v20
	v_cmp_gt_f32_e32 vcc, s6, v20
	s_lshl_b32 s13, s12, 12
	s_add_u32 s16, s2, s13
	v_cndmask_b32_e32 v20, v20, v21, vcc
	v_rsq_f32_e32 v22, v20
	s_addc_u32 s17, s3, 0
	v_lshlrev_b32_e32 v24, 16, v90
	v_mul_f32_e32 v21, 0x45800000, v22
	v_and_b32_e32 v25, 0xffff0000, v90
	v_cndmask_b32_e32 v22, v22, v21, vcc
	v_lshlrev_b32_e32 v26, 16, v91
	v_and_b32_e32 v27, 0xffff0000, v91
	v_lshlrev_b32_e32 v28, 16, v92
	v_and_b32_e32 v29, 0xffff0000, v92
	v_lshlrev_b32_e32 v30, 16, v93
	v_and_b32_e32 v31, 0xffff0000, v93
	v_lshlrev_b32_e32 v32, 16, v94
	v_and_b32_e32 v33, 0xffff0000, v94
	v_lshlrev_b32_e32 v34, 16, v95
	v_and_b32_e32 v35, 0xffff0000, v95
	v_lshlrev_b32_e32 v36, 16, v96
	v_and_b32_e32 v37, 0xffff0000, v96
	v_lshlrev_b32_e32 v38, 16, v97
	v_and_b32_e32 v39, 0xffff0000, v97
	v_pk_mul_f32 v[24:25], v[22:23], v[24:25] op_sel_hi:[0,1]
	v_pk_mul_f32 v[26:27], v[22:23], v[26:27] op_sel_hi:[0,1]
	v_pk_mul_f32 v[28:29], v[22:23], v[28:29] op_sel_hi:[0,1]
	v_pk_mul_f32 v[30:31], v[22:23], v[30:31] op_sel_hi:[0,1]
	v_pk_mul_f32 v[32:33], v[22:23], v[32:33] op_sel_hi:[0,1]
	v_pk_mul_f32 v[34:35], v[22:23], v[34:35] op_sel_hi:[0,1]
	v_pk_mul_f32 v[36:37], v[22:23], v[36:37] op_sel_hi:[0,1]
	v_pk_mul_f32 v[38:39], v[22:23], v[38:39] op_sel_hi:[0,1]
	v_pk_mul_f32 v[24:25], v[64:65], v[24:25]
	v_pk_mul_f32 v[26:27], v[66:67], v[26:27]
	v_pk_mul_f32 v[28:29], v[68:69], v[28:29]
	v_pk_mul_f32 v[30:31], v[70:71], v[30:31]
	v_pk_mul_f32 v[32:33], v[72:73], v[32:33]
	v_pk_mul_f32 v[34:35], v[74:75], v[34:35]
	v_pk_mul_f32 v[36:37], v[76:77], v[36:37]
	v_pk_mul_f32 v[38:39], v[78:79], v[38:39]
	global_store_dwordx4 v9, v[24:27], s[16:17] nt
	global_store_dwordx4 v9, v[28:31], s[16:17] offset:16 nt
	global_store_dwordx4 v9, v[32:35], s[16:17] offset:2048 nt
	global_store_dwordx4 v9, v[36:39], s[16:17] offset:2064 nt
; DI float bflo(unsigned w) { return __uint_as_float(w << 16); }
; DI float bfhi(unsigned w) { return __uint_as_float(w & 0xffff0000u); }
; __global__ void __launch_bounds__(512, 2) fwd_mega(Params p) {
;     ...
;   { int tidf = threadIdx.x; asm volatile("" : "+v"(tidf)); const int lane = tidf & 63; const int gw = bid * 8 + (tidf >> 6);
;     for (int m = gw; m < MTOK; m += 2 * NGW) {
;       const int m2 = (m + NGW < MTOK) ? m + NGW : m;
;       const float q1 = ssq[3 * MTOK + m], q2 = ssq[3 * MTOK + m2];
;       const u32x4* xr = (const u32x4*)(XB + (size_t)m * DM) + lane; const u32x4* xr2 = (const u32x4*)(XB + (size_t)m2 * DM) + lane;
;       const u32x4 va0 = xr[0], va1 = xr[64], vb0 = xr2[0], vb1 = xr2[64];
;       const f32x4* gr = (const f32x4*)p.final_norm;
; #pragma unroll
;       for (int rr = 0; rr < 2; ++rr) {
;         if (rr == 1 && m2 == m) break;
;         const float rstd = rsqrtf((rr ? q2 : q1) * (1.f / DM) + EPSN);
;         f32x4* orow = (f32x4*)(p.out + (size_t)(rr ? m2 : m) * DM);
; #pragma unroll
;         for (int j = 0; j < 2; ++j) { const u32x4 v = rr ? (j ? vb1 : vb0) : (j ? va1 : va0); const int c4 = (64 * j + lane) * 2;
;           const f32x4 g0 = gr[c4], g1 = gr[c4 + 1];
;           f32x4 o0, o1; o0[0] = bflo(v.x) * rstd * g0[0]; o0[1] = bfhi(v.x) * rstd * g0[1]; o0[2] = bflo(v.y) * rstd * g0[2]; o0[3] = bfhi(v.y) * rstd * g0[3];
;           o1[0] = bflo(v.z) * rstd * g1[0]; o1[1] = bfhi(v.z) * rstd * g1[1]; o1[2] = bflo(v.w) * rstd * g1[2]; o1[3] = bfhi(v.w) * rstd * g1[3];
;           __builtin_nontemporal_store(o0, &orow[c4]); __builtin_nontemporal_store(o1, &orow[c4 + 1]); }
;       }
;     } }
.Lfin_skip_2:
	s_cmp_gt_u32 s9, 0xffff
	s_cbranch_scc1 .LBB0_1415
	s_add_u32 s8, s9, s18
	s_min_u32 s12, s8, 0xffff
	s_lshl_b32 s13, s12, 11
	s_add_u32 s14, s72, s13
	s_addc_u32 s15, s73, 0
	global_load_dwordx4 v[80:83], v8, s[14:15]
	global_load_dwordx4 v[84:87], v8, s[14:15] offset:1024
	s_lshl_b32 s13, s12, 2
	s_add_u32 s14, s10, s13
	s_addc_u32 s15, s11, 0
	global_load_dword v88, v10, s[14:15]
	s_mul_i32 s12, s48, 1
	s_add_u32 s12, s12, s8
	s_min_u32 s12, s12, 0xffff
	s_lshl_b32 s13, s12, 11
	s_add_u32 s14, s72, s13
	s_addc_u32 s15, s73, 0
	global_load_dwordx4 v[90:93], v8, s[14:15]
	global_load_dwordx4 v[94:97], v8, s[14:15] offset:1024
	s_lshl_b32 s13, s12, 2
	s_add_u32 s14, s10, s13
	s_addc_u32 s15, s11, 0
	global_load_dword v98, v10, s[14:15]
	s_waitcnt vmcnt(6)
	s_mov_b32 s12, s9
	v_fmamk_f32 v20, v128, 0x3a800000, v18
	v_mul_f32_e32 v21, 0x4b800000, v20
	v_cmp_gt_f32_e32 vcc, s6, v20
	s_lshl_b32 s13, s12, 12
	s_add_u32 s16, s2, s13
	v_cndmask_b32_e32 v20, v20, v21, vcc
	v_rsq_f32_e32 v22, v20
	s_addc_u32 s17, s3, 0
	v_lshlrev_b32_e32 v24, 16, v120
	v_mul_f32_e32 v21, 0x45800000, v22
	v_and_b32_e32 v25, 0xffff0000, v120
	v_cndmask_b32_e32 v22, v22, v21, vcc
	v_lshlrev_b32_e32 v26, 16, v121
	v_and_b32_e32 v27, 0xffff0000, v121
	v_lshlrev_b32_e32 v28, 16, v122
	v_and_b32_e32 v29, 0xffff0000, v122
	v_lshlrev_b32_e32 v30, 16, v123
	v_and_b32_e32 v31, 0xffff0000, v123
	v_lshlrev_b32_e32 v32, 16, v124
	v_and_b32_e32 v33, 0xffff0000, v124
	v_lshlrev_b32_e32 v34, 16, v125
	v_and_b32_e32 v35, 0xffff0000, v125
	v_lshlrev_b32_e32 v36, 16, v126
	v_and_b32_e32 v37, 0xffff0000, v126
	v_lshlrev_b32_e32 v38, 16, v127
	v_and_b32_e32 v39, 0xffff0000, v127
	v_pk_mul_f32 v[24:25], v[22:23], v[24:25] op_sel_hi:[0,1]
	v_pk_mul_f32 v[26:27], v[22:23], v[26:27] op_sel_hi:[0,1]
	v_pk_mul_f32 v[28:29], v[22:23], v[28:29] op_sel_hi:[0,1]
	v_pk_mul_f32 v[30:31], v[22:23], v[30:31] op_sel_hi:[0,1]
	v_pk_mul_f32 v[32:33], v[22:23], v[32:33] op_sel_hi:[0,1]
	v_pk_mul_f32 v[34:35], v[22:23], v[34:35] op_sel_hi:[0,1]
	v_pk_mul_f32 v[36:37], v[22:23], v[36:37] op_sel_hi:[0,1]
	v_pk_mul_f32 v[38:39], v[22:23], v[38:39] op_sel_hi:[0,1]
	v_pk_mul_f32 v[24:25], v[64:65], v[24:25]
	v_pk_mul_f32 v[26:27], v[66:67], v[26:27]
	v_pk_mul_f32 v[28:29], v[68:69], v[28:29]
	v_pk_mul_f32 v[30:31], v[70:71], v[30:31]
	v_pk_mul_f32 v[32:33], v[72:73], v[32:33]
	v_pk_mul_f32 v[34:35], v[74:75], v[34:35]
	v_pk_mul_f32 v[36:37], v[76:77], v[36:37]
	v_pk_mul_f32 v[38:39], v[78:79], v[38:39]
	global_store_dwordx4 v9, v[24:27], s[16:17] nt
	global_store_dwordx4 v9, v[28:31], s[16:17] offset:16 nt
	global_store_dwordx4 v9, v[32:35], s[16:17] offset:2048 nt
	global_store_dwordx4 v9, v[36:39], s[16:17] offset:2064 nt
	s_mul_i32 s12, s48, 1
	s_add_u32 s12, s12, s9
	s_cmp_gt_u32 s12, 0xffff
	s_cbranch_scc1 .Lfin_skip_4
	v_fmamk_f32 v20, v138, 0x3a800000, v18
	v_mul_f32_e32 v21, 0x4b800000, v20
	v_cmp_gt_f32_e32 vcc, s6, v20
	s_lshl_b32 s13, s12, 12
	s_add_u32 s16, s2, s13
	v_cndmask_b32_e32 v20, v20, v21, vcc
	v_rsq_f32_e32 v22, v20
	s_addc_u32 s17, s3, 0
	v_lshlrev_b32_e32 v24, 16, v130
	v_mul_f32_e32 v21, 0x45800000, v22
	v_and_b32_e32 v25, 0xffff0000, v130
	v_cndmask_b32_e32 v22, v22, v21, vcc
	v_lshlrev_b32_e32 v26, 16, v131
	v_and_b32_e32 v27, 0xffff0000, v131
	v_lshlrev_b32_e32 v28, 16, v132
	v_and_b32_e32 v29, 0xffff0000, v132
	v_lshlrev_b32_e32 v30, 16, v133
	v_and_b32_e32 v31, 0xffff0000, v133
	v_lshlrev_b32_e32 v32, 16, v134
	v_and_b32_e32 v33, 0xffff0000, v134
	v_lshlrev_b32_e32 v34, 16, v135
	v_and_b32_e32 v35, 0xffff0000, v135
	v_lshlrev_b32_e32 v36, 16, v136
	v_and_b32_e32 v37, 0xffff0000, v136
	v_lshlrev_b32_e32 v38, 16, v137
	v_and_b32_e32 v39, 0xffff0000, v137
	v_pk_mul_f32 v[24:25], v[22:23], v[24:25] op_sel_hi:[0,1]
	v_pk_mul_f32 v[26:27], v[22:23], v[26:27] op_sel_hi:[0,1]
	v_pk_mul_f32 v[28:29], v[22:23], v[28:29] op_sel_hi:[0,1]
	v_pk_mul_f32 v[30:31], v[22:23], v[30:31] op_sel_hi:[0,1]
	v_pk_mul_f32 v[32:33], v[22:23], v[32:33] op_sel_hi:[0,1]
	v_pk_mul_f32 v[34:35], v[22:23], v[34:35] op_sel_hi:[0,1]
	v_pk_mul_f32 v[36:37], v[22:23], v[36:37] op_sel_hi:[0,1]
	v_pk_mul_f32 v[38:39], v[22:23], v[38:39] op_sel_hi:[0,1]
	v_pk_mul_f32 v[24:25], v[64:65], v[24:25]
	v_pk_mul_f32 v[26:27], v[66:67], v[26:27]
	v_pk_mul_f32 v[28:29], v[68:69], v[28:29]
	v_pk_mul_f32 v[30:31], v[70:71], v[30:31]
	v_pk_mul_f32 v[32:33], v[72:73], v[32:33]
	v_pk_mul_f32 v[34:35], v[74:75], v[34:35]
	v_pk_mul_f32 v[36:37], v[76:77], v[36:37]
	v_pk_mul_f32 v[38:39], v[78:79], v[38:39]
	global_store_dwordx4 v9, v[24:27], s[16:17] nt
	global_store_dwordx4 v9, v[28:31], s[16:17] offset:16 nt
	global_store_dwordx4 v9, v[32:35], s[16:17] offset:2048 nt
	global_store_dwordx4 v9, v[36:39], s[16:17] offset:2064 nt
